# prologue phase weight-conversion items (FFN1-in weights with gains): the 8 row loads and gain loads issued together, as in the FFN1-in phase idle-slot items
# speedup vs baseline: 1.0078x; 1.0057x over previous
; #define LAS __attribute__((address_space(3)))
; __device__ __forceinline__ unsigned pk2(float lo, float hi) { return pg8::cvt_pk_bf16(lo, hi); }
; #define AIN(i) arg_in(i)
; __device__ __forceinline__ void transpose_tile_block(int kind, const float* W, int N, int K, int ND, bf16* WT, const float* gk, int item, LAS unsigned char* lds, int tid) {
;     ...
;     LAS float* T = (LAS float*)lds;
;     __syncthreads();
; #pragma unroll
;     for (int r = 0; r < 8; ++r) { const int id = tid + NTHREADS * r, row = id >> 6, cv = id & 63, col = cv * 4;
;         f32x4 v = (f32x4){0.f, 0.f, 0.f, 0.f};
;         if (col < nvalid) { const int src = (col < 128) ? srcA + col : srcB + (col - 128); v = *(const f32x4*)(W + (size_t)(k0 + row) * N + src); }
;         const float g = (gk ? gk[k0 + row] : 1.0f) * cs;
;         *(LAS f32x4*)(T + row * LP + col) = v * g; }
;     __syncthreads();
; #pragma unroll
;     for (int r = 0; r < 4; ++r) { const int id = tid + NTHREADS * r, n = id >> 3, k8 = id & 7; const LAS float* s = T + (k8 * 8) * LP + n;
;         u32x4 o; o.x = pk2(s[0 * LP], s[1 * LP]); o.y = pk2(s[2 * LP], s[3 * LP]); o.z = pk2(s[4 * LP], s[5 * LP]); o.w = pk2(s[6 * LP], s[7 * LP]);
;         *(u32x4*)(WT + (size_t)(drow0 + n) * K + k0 + 8 * k8) = o; }
; __global__ void __launch_bounds__(NTHREADS, 2) fwd_megakernel(Args a) {
;     ...
;         for (int it = bx; it < 16 * 22; it += G) transpose_tile_block(1, AIN(6), 5632, 1024, 5632, W1T, AIN(5), it, lds, tid);
.LP0_store:
	s_waitcnt lgkmcnt(0)
	s_barrier
	ds_read_b32 v2, v31
	ds_read_b32 v3, v31 offset:1040
	ds_read_b32 v4, v31 offset:2080
	ds_read_b32 v5, v31 offset:3120
	ds_read_b32 v8, v31 offset:4160
	ds_read_b32 v9, v31 offset:5200
	ds_read_b32 v10, v31 offset:6240
	ds_read_b32 v11, v31 offset:7280
	s_mul_i32 s4, s17, 0xffffea00
	s_add_i32 s4, s4, s2
	s_waitcnt lgkmcnt(6)
	v_cvt_pk_bf16_f32 v2, v2, v3
	s_waitcnt lgkmcnt(4)
	v_cvt_pk_bf16_f32 v3, v4, v5
	s_waitcnt lgkmcnt(2)
	v_cvt_pk_bf16_f32 v4, v8, v9
	s_waitcnt lgkmcnt(0)
	v_cvt_pk_bf16_f32 v5, v10, v11
	v_add_u32_e32 v8, s4, v30
	ds_read_b32 v10, v33
	ds_read_b32 v11, v33 offset:1040
	ds_read_b32 v12, v33 offset:2080
	ds_read_b32 v13, v33 offset:3120
	ds_read_b32 v16, v33 offset:4160
	ds_read_b32 v17, v33 offset:5200
	ds_read_b32 v18, v33 offset:6240
	ds_read_b32 v19, v33 offset:7280
	s_ashr_i32 s9, s8, 31
	v_ashrrev_i32_e32 v9, 31, v8
	v_lshl_add_u64 v[6:7], s[8:9], 1, v[14:15]
	v_lshlrev_b64 v[8:9], 11, v[8:9]
	v_lshl_add_u64 v[8:9], v[6:7], 0, v[8:9]
	global_store_dwordx4 v[8:9], v[2:5], off
	v_add_u32_e32 v8, s4, v32
	v_ashrrev_i32_e32 v9, 31, v8
	s_waitcnt lgkmcnt(6)
	v_cvt_pk_bf16_f32 v2, v10, v11
	s_waitcnt lgkmcnt(4)
	v_cvt_pk_bf16_f32 v3, v12, v13
	s_waitcnt lgkmcnt(2)
	v_cvt_pk_bf16_f32 v4, v16, v17
	s_waitcnt lgkmcnt(0)
	v_cvt_pk_bf16_f32 v5, v18, v19
	ds_read_b32 v10, v35
	ds_read_b32 v11, v35 offset:1040
	ds_read_b32 v12, v35 offset:2080
	ds_read_b32 v13, v35 offset:3120
	ds_read_b32 v16, v35 offset:4160
	ds_read_b32 v17, v35 offset:5200
	ds_read_b32 v18, v35 offset:6240
	ds_read_b32 v19, v35 offset:7280
	v_lshlrev_b64 v[8:9], 11, v[8:9]
	v_lshl_add_u64 v[8:9], v[6:7], 0, v[8:9]
	global_store_dwordx4 v[8:9], v[2:5], off
	v_add_u32_e32 v8, s4, v34
	v_ashrrev_i32_e32 v9, 31, v8
	s_waitcnt lgkmcnt(6)
	v_cvt_pk_bf16_f32 v2, v10, v11
	s_waitcnt lgkmcnt(4)
	v_cvt_pk_bf16_f32 v3, v12, v13
	s_waitcnt lgkmcnt(2)
	v_cvt_pk_bf16_f32 v4, v16, v17
	s_waitcnt lgkmcnt(0)
	v_cvt_pk_bf16_f32 v5, v18, v19
	v_lshlrev_b64 v[8:9], 11, v[8:9]
	ds_read_b32 v10, v37
	ds_read_b32 v11, v37 offset:1040
	ds_read_b32 v12, v37 offset:2080
	ds_read_b32 v13, v37 offset:3120
	ds_read_b32 v16, v37 offset:4160
	ds_read_b32 v17, v37 offset:5200
	ds_read_b32 v18, v37 offset:6240
	ds_read_b32 v19, v37 offset:7280
	v_lshl_add_u64 v[8:9], v[6:7], 0, v[8:9]
	global_store_dwordx4 v[8:9], v[2:5], off
	v_add_u32_e32 v8, s4, v36
	v_ashrrev_i32_e32 v9, 31, v8
	v_lshlrev_b64 v[8:9], 11, v[8:9]
	s_add_i32 s16, s16, s70
	s_add_i32 s2, s2, s3
	s_waitcnt lgkmcnt(6)
	v_cvt_pk_bf16_f32 v2, v10, v11
	s_waitcnt lgkmcnt(4)
	v_cvt_pk_bf16_f32 v3, v12, v13
	s_waitcnt lgkmcnt(2)
	v_cvt_pk_bf16_f32 v4, v16, v17
	s_waitcnt lgkmcnt(0)
	v_cvt_pk_bf16_f32 v5, v18, v19
	v_lshl_add_u64 v[6:7], v[6:7], 0, v[8:9]
	s_cmpk_gt_i32 s16, 0x15f
	v_add_u32_e32 v38, s14, v38
	global_store_dwordx4 v[6:7], v[2:5], off
	s_cbranch_scc1 .LBB0_24
.LBB0_8:
	s_mov_b64 s[4:5], s[90:91]
	s_mov_b64 s[8:9], s[90:91]
	s_load_dwordx2 s[4:5], s[4:5], 0x30
	s_load_dwordx2 s[10:11], s[8:9], 0x28
	s_mul_hi_i32 s8, s16, 0x2e8ba2e9
	s_lshr_b32 s9, s8, 31
	s_ashr_i32 s17, s8, 2
	s_add_i32 s17, s17, s9
	s_mul_i32 s9, s17, 0xfffff500
	v_add_u32_e32 v2, s9, v38
	s_lshl_b32 s8, s17, 6
	v_ashrrev_i32_e32 v3, 31, v2
	s_waitcnt lgkmcnt(0)
	v_lshl_add_u64 v[16:17], v[2:3], 2, s[4:5]
	v_add_u32_e32 v2, s8, v22
	v_mad_i64_i32 v[4:5], s[4:5], v2, s15, v[16:17]
	s_barrier
	v_add_u32_e32 v120, s8, v22
	v_add_u32_e32 v121, s8, v23
	v_add_u32_e32 v122, s8, v24
	v_add_u32_e32 v123, s8, v25
	v_add_u32_e32 v124, s8, v26
	v_add_u32_e32 v125, s8, v27
	v_add_u32_e32 v126, s8, v28
	v_add_u32_e32 v127, s8, v29
	v_mad_i64_i32 v[128:129], s[12:13], v120, s15, v[16:17]
	global_load_dwordx4 v[88:91], v[128:129], off
	v_mad_i64_i32 v[128:129], s[12:13], v121, s15, v[16:17]
	global_load_dwordx4 v[92:95], v[128:129], off
	v_mad_i64_i32 v[128:129], s[12:13], v122, s15, v[16:17]
	global_load_dwordx4 v[96:99], v[128:129], off
	v_mad_i64_i32 v[128:129], s[12:13], v123, s15, v[16:17]
	global_load_dwordx4 v[100:103], v[128:129], off
	v_mad_i64_i32 v[128:129], s[12:13], v124, s15, v[16:17]
	global_load_dwordx4 v[104:107], v[128:129], off
	v_mad_i64_i32 v[128:129], s[12:13], v125, s15, v[16:17]
	global_load_dwordx4 v[108:111], v[128:129], off
	v_mad_i64_i32 v[128:129], s[12:13], v126, s15, v[16:17]
	global_load_dwordx4 v[112:115], v[128:129], off
	v_mad_i64_i32 v[128:129], s[12:13], v127, s15, v[16:17]
	global_load_dwordx4 v[116:119], v[128:129], off
	s_cmp_eq_u64 s[10:11], 0
	s_cbranch_scc1 .Lcvp0_none
	v_mov_b32_e32 v86, v120
	v_ashrrev_i32_e32 v87, 31, v86
	v_lshl_add_u64 v[130:131], v[86:87], 2, s[10:11]
	global_load_dword v120, v[130:131], off
	v_mov_b32_e32 v86, v121
	v_ashrrev_i32_e32 v87, 31, v86
	v_lshl_add_u64 v[130:131], v[86:87], 2, s[10:11]
	global_load_dword v121, v[130:131], off
	v_mov_b32_e32 v86, v122
	v_ashrrev_i32_e32 v87, 31, v86
	v_lshl_add_u64 v[130:131], v[86:87], 2, s[10:11]
	global_load_dword v122, v[130:131], off
	v_mov_b32_e32 v86, v123
	v_ashrrev_i32_e32 v87, 31, v86
	v_lshl_add_u64 v[130:131], v[86:87], 2, s[10:11]
	global_load_dword v123, v[130:131], off
	v_mov_b32_e32 v86, v124
	v_ashrrev_i32_e32 v87, 31, v86
	v_lshl_add_u64 v[130:131], v[86:87], 2, s[10:11]
	global_load_dword v124, v[130:131], off
	v_mov_b32_e32 v86, v125
	v_ashrrev_i32_e32 v87, 31, v86
	v_lshl_add_u64 v[130:131], v[86:87], 2, s[10:11]
	global_load_dword v125, v[130:131], off
	v_mov_b32_e32 v86, v126
	v_ashrrev_i32_e32 v87, 31, v86
	v_lshl_add_u64 v[130:131], v[86:87], 2, s[10:11]
	global_load_dword v126, v[130:131], off
	v_mov_b32_e32 v86, v127
	v_ashrrev_i32_e32 v87, 31, v86
	v_lshl_add_u64 v[130:131], v[86:87], 2, s[10:11]
	global_load_dword v127, v[130:131], off
	s_branch .Lcvp0_go

; #define LAS __attribute__((address_space(3)))
; __device__ __forceinline__ void transpose_tile_block(int kind, const float* W, int N, int K, int ND, bf16* WT, const float* gk, int item, LAS unsigned char* lds, int tid) {
;     ...
;     for (int r = 0; r < 8; ++r) { const int id = tid + NTHREADS * r, row = id >> 6, cv = id & 63, col = cv * 4;
;         f32x4 v = (f32x4){0.f, 0.f, 0.f, 0.f};
;         if (col < nvalid) { const int src = (col < 128) ? srcA + col : srcB + (col - 128); v = *(const f32x4*)(W + (size_t)(k0 + row) * N + src); }
;         const float g = (gk ? gk[k0 + row] : 1.0f) * cs;
;         *(LAS f32x4*)(T + row * LP + col) = v * g; }
.Lcvp0_go:
	s_waitcnt vmcnt(0)
	v_mul_f32_e32 v88, v88, v120
	v_mul_f32_e32 v89, v89, v120
	v_mul_f32_e32 v90, v90, v120
	v_mul_f32_e32 v91, v91, v120
	ds_write_b128 v39, v[88:91]
	v_mul_f32_e32 v92, v92, v121
	v_mul_f32_e32 v93, v93, v121
	v_mul_f32_e32 v94, v94, v121
	v_mul_f32_e32 v95, v95, v121
	ds_write_b128 v40, v[92:95]
	v_mul_f32_e32 v96, v96, v122
	v_mul_f32_e32 v97, v97, v122
	v_mul_f32_e32 v98, v98, v122
	v_mul_f32_e32 v99, v99, v122
	ds_write_b128 v41, v[96:99]
	v_mul_f32_e32 v100, v100, v123
	v_mul_f32_e32 v101, v101, v123
	v_mul_f32_e32 v102, v102, v123
	v_mul_f32_e32 v103, v103, v123
	ds_write_b128 v42, v[100:103]
	v_mul_f32_e32 v104, v104, v124
	v_mul_f32_e32 v105, v105, v124
	v_mul_f32_e32 v106, v106, v124
	v_mul_f32_e32 v107, v107, v124
	ds_write_b128 v43, v[104:107]
	v_mul_f32_e32 v108, v108, v125
	v_mul_f32_e32 v109, v109, v125
	v_mul_f32_e32 v110, v110, v125
	v_mul_f32_e32 v111, v111, v125
	ds_write_b128 v44, v[108:111]
	v_mul_f32_e32 v112, v112, v126
	v_mul_f32_e32 v113, v113, v126
	v_mul_f32_e32 v114, v114, v126
	v_mul_f32_e32 v115, v115, v126
	ds_write_b128 v45, v[112:115]
	v_mul_f32_e32 v116, v116, v127
	v_mul_f32_e32 v117, v117, v127
	v_mul_f32_e32 v118, v118, v127
	v_mul_f32_e32 v119, v119, v127
	ds_write_b128 v46, v[116:119]
	s_branch .LP0_store

; template <class Epi, class Sched, bool ALIGN_EPI = false, bool SP2 = false>
; __device__ __forceinline__ void gemm_phase(PG8_LAS unsigned char* lds, const Gemm g, const Sched& S, const Epi& E, const int tid_arg) {
;     ...
; #pragma unroll
;         for (int a = 0; a < 2; ++a)
; #pragma unroll
;             for (int b = 0; b < 2; ++b)
; #pragma unroll
;                 for (int m = 0; m < 4; ++m)
; #pragma unroll
;                     for (int n = 0; n < 2; ++n) acc[a][b][m][n] = (f32x4){0.f, 0.f, 0.f, 0.f};
.LBB0_95:
	s_ashr_i32 s21, s20, 31
	s_lshl_b64 s[22:23], s[20:21], 19
	s_add_u32 s22, s1, s22
	s_addc_u32 s23, s2, s23
	s_and_b64 s[24:25], s[6:7], exec
	s_cselect_b32 s21, s23, s29
	s_cselect_b32 s45, s22, s28
	s_ashr_i32 s19, s18, 31
	s_lshl_b64 s[24:25], s[18:19], 19
	s_add_u32 s24, s12, s24
	s_addc_u32 s25, s13, s25
	s_and_b64 s[34:35], s[6:7], exec
	s_cselect_b32 s19, s25, s31
	s_cselect_b32 s46, s24, s30
	s_add_u32 s28, s28, 0x40080
	s_addc_u32 s29, s29, 0
	s_add_u32 s47, s30, 0x100
	v_mov_b32_e32 v2, 0
	s_addc_u32 s48, s31, 0
	s_mov_b32 s49, -2
	v_mov_b32_e32 v3, v2
	v_mov_b32_e32 v4, v2
	v_mov_b32_e32 v5, v2
	v_mov_b32_e32 v6, v2
	v_mov_b32_e32 v7, v2
	v_mov_b32_e32 v8, v2
	v_mov_b32_e32 v9, v2
	v_mov_b32_e32 v18, v2
	v_mov_b32_e32 v19, v2
	v_mov_b32_e32 v20, v2
	v_mov_b32_e32 v21, v2
	v_mov_b32_e32 v22, v2
	v_mov_b32_e32 v23, v2
	v_mov_b32_e32 v24, v2
	v_mov_b32_e32 v25, v2
	v_mov_b32_e32 v34, v2
	v_mov_b32_e32 v35, v2
	v_mov_b32_e32 v36, v2
	v_mov_b32_e32 v37, v2
	v_mov_b32_e32 v38, v2
	v_mov_b32_e32 v39, v2
	v_mov_b32_e32 v40, v2
	v_mov_b32_e32 v41, v2
	v_mov_b32_e32 v50, v2
	v_mov_b32_e32 v51, v2
	v_mov_b32_e32 v52, v2
	v_mov_b32_e32 v53, v2
	v_mov_b32_e32 v54, v2
	v_mov_b32_e32 v55, v2
	v_mov_b32_e32 v56, v2
	v_mov_b32_e32 v57, v2
	v_mov_b32_e32 v10, v2
	v_mov_b32_e32 v11, v2
	v_mov_b32_e32 v12, v2
	v_mov_b32_e32 v13, v2
	v_mov_b32_e32 v14, v2
	v_mov_b32_e32 v15, v2
	v_mov_b32_e32 v16, v2
	v_mov_b32_e32 v17, v2
	v_mov_b32_e32 v26, v2
	v_mov_b32_e32 v27, v2
	v_mov_b32_e32 v28, v2
	v_mov_b32_e32 v29, v2
	v_mov_b32_e32 v30, v2
	v_mov_b32_e32 v31, v2
	v_mov_b32_e32 v32, v2
	v_mov_b32_e32 v33, v2
	v_mov_b32_e32 v42, v2
	v_mov_b32_e32 v43, v2
	v_mov_b32_e32 v44, v2
	v_mov_b32_e32 v45, v2
	v_mov_b32_e32 v46, v2
	v_mov_b32_e32 v47, v2
	v_mov_b32_e32 v48, v2
	v_mov_b32_e32 v49, v2
	v_mov_b32_e32 v58, v2
	v_mov_b32_e32 v59, v2
	v_mov_b32_e32 v60, v2
	v_mov_b32_e32 v61, v2
	v_mov_b32_e32 v62, v2
	v_mov_b32_e32 v63, v2
	v_mov_b32_e32 v64, v2
	v_mov_b32_e32 v65, v2
	v_mov_b32_e32 v66, v2
	v_mov_b32_e32 v67, v2
	v_mov_b32_e32 v68, v2
	v_mov_b32_e32 v69, v2
	v_mov_b32_e32 v70, v2
	v_mov_b32_e32 v71, v2
	v_mov_b32_e32 v72, v2
	v_mov_b32_e32 v73, v2
	v_mov_b32_e32 v82, v2
	v_mov_b32_e32 v83, v2
	v_mov_b32_e32 v84, v2
	v_mov_b32_e32 v85, v2
	v_mov_b32_e32 v86, v2
	v_mov_b32_e32 v87, v2
	v_mov_b32_e32 v88, v2
	v_mov_b32_e32 v89, v2
	v_mov_b32_e32 v98, v2
	v_mov_b32_e32 v99, v2
	v_mov_b32_e32 v100, v2
	v_mov_b32_e32 v101, v2
	v_mov_b32_e32 v102, v2
	v_mov_b32_e32 v103, v2
	v_mov_b32_e32 v104, v2
	v_mov_b32_e32 v105, v2
	v_mov_b32_e32 v114, v2
	v_mov_b32_e32 v115, v2
	v_mov_b32_e32 v116, v2
	v_mov_b32_e32 v117, v2
	v_mov_b32_e32 v118, v2
	v_mov_b32_e32 v119, v2
	v_mov_b32_e32 v120, v2
	v_mov_b32_e32 v121, v2
	v_mov_b32_e32 v74, v2
	v_mov_b32_e32 v75, v2
	v_mov_b32_e32 v76, v2
	v_mov_b32_e32 v77, v2
	v_mov_b32_e32 v78, v2
	v_mov_b32_e32 v79, v2
	v_mov_b32_e32 v80, v2
	v_mov_b32_e32 v81, v2
	v_mov_b32_e32 v90, v2
	v_mov_b32_e32 v91, v2
	v_mov_b32_e32 v92, v2
	v_mov_b32_e32 v93, v2
	v_mov_b32_e32 v94, v2
	v_mov_b32_e32 v95, v2
	v_mov_b32_e32 v96, v2
	v_mov_b32_e32 v97, v2
	v_mov_b32_e32 v106, v2
	v_mov_b32_e32 v107, v2
	v_mov_b32_e32 v108, v2
	v_mov_b32_e32 v109, v2
	v_mov_b32_e32 v110, v2
	v_mov_b32_e32 v111, v2
	v_mov_b32_e32 v112, v2
	v_mov_b32_e32 v113, v2
	v_mov_b32_e32 v122, v2
	v_mov_b32_e32 v123, v2
	v_mov_b32_e32 v124, v2
	v_mov_b32_e32 v125, v2
	v_mov_b32_e32 v126, v2
	v_mov_b32_e32 v127, v2
	v_mov_b32_e32 v128, v2
	v_mov_b32_e32 v129, v2
	s_nop 0
	s_nop 0
	s_nop 0
	s_nop 0
	s_nop 0
	s_nop 0
	s_nop 0
	s_nop 0
